# dead-work removal in the in-proj GEMM: MFMA groups of the dt N-tile that multiply all-zero weight columns are skipped with wave-uniform branches (bj=1 groups for all waves, bj=0 groups for waves with
# baseline (speedup 1.0000x reference)
.LBB0_1658:
	s_add_u32 s10, s34, s44
	s_addc_u32 s11, s35, s45
	s_add_u32 s10, s10, 0x100
	s_addc_u32 s11, s11, 0
	s_add_u32 s72, s33, s44
	s_addc_u32 s74, s48, s45
	s_add_i32 s75, 0, 0x10000
	s_cmpk_eq_i32 s44, 0x700
	s_cselect_b32 s11, s29, s11
	s_cselect_b32 s10, s28, s10
	s_cselect_b32 s81, s31, s74
	s_cselect_b32 s80, s30, s72
	s_add_i32 s72, 0, 0x14000
	v_add_u32_e32 v146, s75, v184
	v_add_u32_e32 v158, s72, v184
	ds_read_b128 v[134:137], v146
	ds_read_b128 v[138:141], v146 offset:1024
	ds_read_b128 v[142:145], v146 offset:2048
	ds_read_b128 v[146:149], v146 offset:3072
	ds_read_b128 v[150:153], v158
	ds_read_b128 v[154:157], v158 offset:1024
	ds_read_b128 v[178:181], v158 offset:2048
	ds_read_b128 v[186:189], v158 offset:3072
	v_lshl_add_u64 v[158:159], v[130:131], 0, s[44:45]
	s_add_i32 m0, s14, 0xc000
	ds_read_b128 v[204:207], v185
	ds_read_b128 v[208:211], v185 offset:1024
	ds_read_b128 v[212:215], v185 offset:2048
	ds_read_b128 v[216:219], v185 offset:3072
	ds_read_b128 v[226:229], v185 offset:4096
	ds_read_b128 v[230:233], v185 offset:5120
	ds_read_b128 v[234:237], v185 offset:6144
	ds_read_b128 v[238:241], v185 offset:7168
	global_load_lds_dwordx4 v[158:159], off
	v_lshl_add_u64 v[158:159], v[132:133], 0, s[44:45]
	s_add_i32 m0, s14, 0xe000
	s_nop 0
	global_load_lds_dwordx4 v[158:159], off
	s_waitcnt vmcnt(8)
	s_waitcnt lgkmcnt(0)
	s_barrier
	s_setprio 1
	s_waitcnt lgkmcnt(0)
	s_cmp_eq_u32 s96, 10
	s_cbranch_scc0 .Ldt_do0
	s_cmp_eq_u64 s[38:39], 0
	s_cbranch_scc1 .Ldt_sk0
.Ldt_do0:
	v_mfma_f32_16x16x32_bf16 v[126:129], v[134:137], v[204:207], v[126:129]
	v_mfma_f32_16x16x32_bf16 v[122:125], v[142:145], v[204:207], v[122:125]
	v_mfma_f32_16x16x32_bf16 v[110:113], v[134:137], v[212:215], v[110:113]
	v_mfma_f32_16x16x32_bf16 v[106:109], v[142:145], v[212:215], v[106:109]
	v_mfma_f32_16x16x32_bf16 v[94:97], v[134:137], v[226:229], v[94:97]
	v_mfma_f32_16x16x32_bf16 v[90:93], v[142:145], v[226:229], v[90:93]
	v_mfma_f32_16x16x32_bf16 v[78:81], v[134:137], v[234:237], v[78:81]
	v_mfma_f32_16x16x32_bf16 v[74:77], v[142:145], v[234:237], v[74:77]
	v_mfma_f32_16x16x32_bf16 v[126:129], v[138:141], v[208:211], v[126:129]
	v_mfma_f32_16x16x32_bf16 v[122:125], v[146:149], v[208:211], v[122:125]
	v_mfma_f32_16x16x32_bf16 v[110:113], v[138:141], v[216:219], v[110:113]
	v_mfma_f32_16x16x32_bf16 v[106:109], v[146:149], v[216:219], v[106:109]
	v_mfma_f32_16x16x32_bf16 v[94:97], v[138:141], v[230:233], v[94:97]
	v_mfma_f32_16x16x32_bf16 v[90:93], v[146:149], v[230:233], v[90:93]
	v_mfma_f32_16x16x32_bf16 v[78:81], v[138:141], v[238:241], v[78:81]
	v_mfma_f32_16x16x32_bf16 v[74:77], v[146:149], v[238:241], v[74:77]
.Ldt_sk0:
	s_setprio 0
	s_setprio 1
	s_cmp_eq_u32 s96, 10
	s_cbranch_scc1 .Ldt_sk1
	v_mfma_f32_16x16x32_bf16 v[118:121], v[150:153], v[204:207], v[118:121]
	v_mfma_f32_16x16x32_bf16 v[114:117], v[178:181], v[204:207], v[114:117]
	v_mfma_f32_16x16x32_bf16 v[102:105], v[150:153], v[212:215], v[102:105]
	v_mfma_f32_16x16x32_bf16 v[98:101], v[178:181], v[212:215], v[98:101]
	v_mfma_f32_16x16x32_bf16 v[86:89], v[150:153], v[226:229], v[86:89]
	v_mfma_f32_16x16x32_bf16 v[82:85], v[178:181], v[226:229], v[82:85]
	v_mfma_f32_16x16x32_bf16 v[70:73], v[150:153], v[234:237], v[70:73]
	v_mfma_f32_16x16x32_bf16 v[66:69], v[178:181], v[234:237], v[66:69]
	v_mfma_f32_16x16x32_bf16 v[118:121], v[154:157], v[208:211], v[118:121]
	v_mfma_f32_16x16x32_bf16 v[114:117], v[186:189], v[208:211], v[114:117]
	v_mfma_f32_16x16x32_bf16 v[102:105], v[154:157], v[216:219], v[102:105]
	v_mfma_f32_16x16x32_bf16 v[98:101], v[186:189], v[216:219], v[98:101]
	v_mfma_f32_16x16x32_bf16 v[86:89], v[154:157], v[230:233], v[86:89]
	v_mfma_f32_16x16x32_bf16 v[82:85], v[186:189], v[230:233], v[82:85]
	v_mfma_f32_16x16x32_bf16 v[70:73], v[154:157], v[238:241], v[70:73]
	v_mfma_f32_16x16x32_bf16 v[66:69], v[186:189], v[238:241], v[66:69]
.Ldt_sk1:
	s_setprio 0
	s_barrier
	s_add_i32 s74, s75, s82
	v_lshl_add_u64 v[158:159], s[80:81], 0, v[162:163]
	s_mov_b32 m0, s74
	ds_read_b128 v[204:207], v185 offset:16384
	ds_read_b128 v[208:211], v185 offset:17408
	ds_read_b128 v[212:215], v185 offset:18432
	ds_read_b128 v[216:219], v185 offset:19456
	ds_read_b128 v[226:229], v185 offset:20480
	ds_read_b128 v[230:233], v185 offset:21504
	ds_read_b128 v[234:237], v185 offset:22528
	ds_read_b128 v[238:241], v185 offset:23552
	global_load_lds_dwordx4 v[158:159], off
	s_add_i32 m0, s74, 0x2000
	v_lshl_add_u64 v[182:183], s[80:81], 0, v[166:167]
	s_add_u32 s80, s80, s4
	s_addc_u32 s81, s81, s5
	s_add_i32 s72, s72, s82
	global_load_lds_dwordx4 v[182:183], off
	v_lshl_add_u64 v[220:221], s[80:81], 0, v[162:163]
	s_mov_b32 m0, s72
	v_lshl_add_u64 v[242:243], s[80:81], 0, v[166:167]
	global_load_lds_dwordx4 v[220:221], off
	s_add_i32 m0, s72, 0x2000
	v_lshl_add_u64 v[244:245], s[10:11], 0, v[160:161]
	global_load_lds_dwordx4 v[242:243], off
	s_mov_b32 m0, s14
	v_lshl_add_u64 v[246:247], s[10:11], 0, v[164:165]
	global_load_lds_dwordx4 v[244:245], off
	s_mov_b32 m0, s15
	s_nop 0
	global_load_lds_dwordx4 v[246:247], off
	s_waitcnt vmcnt(8)
	s_waitcnt lgkmcnt(0)
	s_barrier
	s_setprio 1
	s_waitcnt lgkmcnt(0)
	s_cmp_eq_u32 s96, 10
	s_cbranch_scc0 .Ldt_do2
	s_cmp_eq_u64 s[38:39], 0
	s_cbranch_scc1 .Ldt_sk2
.Ldt_do2:
	v_mfma_f32_16x16x32_bf16 v[62:65], v[134:137], v[204:207], v[62:65]
	v_mfma_f32_16x16x32_bf16 v[58:61], v[142:145], v[204:207], v[58:61]
	v_mfma_f32_16x16x32_bf16 v[46:49], v[134:137], v[212:215], v[46:49]
	v_mfma_f32_16x16x32_bf16 v[42:45], v[142:145], v[212:215], v[42:45]
	v_mfma_f32_16x16x32_bf16 v[30:33], v[134:137], v[226:229], v[30:33]
	v_mfma_f32_16x16x32_bf16 v[26:29], v[142:145], v[226:229], v[26:29]
	v_mfma_f32_16x16x32_bf16 v[14:17], v[134:137], v[234:237], v[14:17]
	v_mfma_f32_16x16x32_bf16 v[10:13], v[142:145], v[234:237], v[10:13]
	v_mfma_f32_16x16x32_bf16 v[62:65], v[138:141], v[208:211], v[62:65]
	v_mfma_f32_16x16x32_bf16 v[58:61], v[146:149], v[208:211], v[58:61]
	v_mfma_f32_16x16x32_bf16 v[46:49], v[138:141], v[216:219], v[46:49]
	v_mfma_f32_16x16x32_bf16 v[42:45], v[146:149], v[216:219], v[42:45]
	v_mfma_f32_16x16x32_bf16 v[30:33], v[138:141], v[230:233], v[30:33]
	v_mfma_f32_16x16x32_bf16 v[26:29], v[146:149], v[230:233], v[26:29]
	v_mfma_f32_16x16x32_bf16 v[14:17], v[138:141], v[238:241], v[14:17]
	v_mfma_f32_16x16x32_bf16 v[10:13], v[146:149], v[238:241], v[10:13]
.Ldt_sk2:
	s_setprio 0
	s_setprio 1
	s_cmp_eq_u32 s96, 10
	s_cbranch_scc1 .Ldt_sk3
	v_mfma_f32_16x16x32_bf16 v[54:57], v[150:153], v[204:207], v[54:57]
	v_mfma_f32_16x16x32_bf16 v[50:53], v[178:181], v[204:207], v[50:53]
	v_mfma_f32_16x16x32_bf16 v[38:41], v[150:153], v[212:215], v[38:41]
	v_mfma_f32_16x16x32_bf16 v[34:37], v[178:181], v[212:215], v[34:37]
	v_mfma_f32_16x16x32_bf16 v[22:25], v[150:153], v[226:229], v[22:25]
	v_mfma_f32_16x16x32_bf16 v[18:21], v[178:181], v[226:229], v[18:21]
	v_mfma_f32_16x16x32_bf16 v[6:9], v[150:153], v[234:237], v[6:9]
	v_mfma_f32_16x16x32_bf16 v[2:5], v[178:181], v[234:237], v[2:5]
	v_mfma_f32_16x16x32_bf16 v[54:57], v[154:157], v[208:211], v[54:57]
	v_mfma_f32_16x16x32_bf16 v[50:53], v[186:189], v[208:211], v[50:53]
	v_mfma_f32_16x16x32_bf16 v[38:41], v[154:157], v[216:219], v[38:41]
	v_mfma_f32_16x16x32_bf16 v[34:37], v[186:189], v[216:219], v[34:37]
	v_mfma_f32_16x16x32_bf16 v[22:25], v[154:157], v[230:233], v[22:25]
	v_mfma_f32_16x16x32_bf16 v[18:21], v[186:189], v[230:233], v[18:21]
	v_mfma_f32_16x16x32_bf16 v[6:9], v[154:157], v[238:241], v[6:9]
	v_mfma_f32_16x16x32_bf16 v[2:5], v[186:189], v[238:241], v[2:5]
.Ldt_sk3:
	s_setprio 0
	s_barrier
	s_add_i32 s72, 0, 0x18000
	s_add_i32 s74, 0, 0x1c000
	v_add_u32_e32 v146, s72, v184
	v_add_u32_e32 v186, s74, v184
	ds_read_b128 v[134:137], v146
	ds_read_b128 v[138:141], v146 offset:1024
	ds_read_b128 v[142:145], v146 offset:2048
	ds_read_b128 v[146:149], v146 offset:3072
	ds_read_b128 v[150:153], v186
	ds_read_b128 v[154:157], v186 offset:1024
	ds_read_b128 v[178:181], v186 offset:2048
	ds_read_b128 v[186:189], v186 offset:3072
	s_add_u32 s10, s10, s4
	s_addc_u32 s11, s11, s5
	s_mov_b32 m0, s16
	v_lshl_add_u64 v[248:249], s[10:11], 0, v[160:161]
	ds_read_b128 v[204:207], v185 offset:32768
	ds_read_b128 v[208:211], v185 offset:33792
	ds_read_b128 v[212:215], v185 offset:34816
	ds_read_b128 v[216:219], v185 offset:35840
	ds_read_b128 v[226:229], v185 offset:36864
	ds_read_b128 v[230:233], v185 offset:37888
	ds_read_b128 v[234:237], v185 offset:38912
	ds_read_b128 v[238:241], v185 offset:39936
	global_load_lds_dwordx4 v[248:249], off
	v_lshl_add_u64 v[248:249], s[10:11], 0, v[164:165]
	s_mov_b32 m0, s17
	s_nop 0
	global_load_lds_dwordx4 v[248:249], off
	s_waitcnt vmcnt(8)
	s_waitcnt lgkmcnt(0)
	s_barrier
	s_setprio 1
	s_waitcnt lgkmcnt(0)
	s_cmp_eq_u32 s96, 10
	s_cbranch_scc0 .Ldt_do4
	s_cmp_eq_u64 s[38:39], 0
	s_cbranch_scc1 .Ldt_sk4

.Ldt_sk5:
	s_setprio 0
	s_barrier
	s_add_i32 s10, s72, s82
	v_lshl_add_u64 v[158:159], v[158:159], 0, s[68:69]
	s_mov_b32 m0, s10
	ds_read_b128 v[204:207], v185 offset:49152
	ds_read_b128 v[208:211], v185 offset:50176
	ds_read_b128 v[212:215], v185 offset:51200
	ds_read_b128 v[216:219], v185 offset:52224
	ds_read_b128 v[226:229], v185 offset:53248
	ds_read_b128 v[230:233], v185 offset:54272
	ds_read_b128 v[234:237], v185 offset:55296
	ds_read_b128 v[238:241], v185 offset:56320
	global_load_lds_dwordx4 v[158:159], off
	v_lshl_add_u64 v[158:159], v[182:183], 0, s[68:69]
	s_add_i32 m0, s10, 0x2000
	s_add_i32 s10, s74, s82
	global_load_lds_dwordx4 v[158:159], off
	v_lshl_add_u64 v[158:159], v[220:221], 0, s[68:69]
	s_mov_b32 m0, s10
	s_nop 0
	global_load_lds_dwordx4 v[158:159], off
	v_lshl_add_u64 v[158:159], v[242:243], 0, s[68:69]
	s_add_i32 m0, s10, 0x2000
	s_nop 0
	global_load_lds_dwordx4 v[158:159], off
	v_lshl_add_u64 v[158:159], v[244:245], 0, s[68:69]
	s_mov_b32 m0, s79
	s_nop 0
	global_load_lds_dwordx4 v[158:159], off
	v_lshl_add_u64 v[158:159], v[246:247], 0, s[68:69]
	s_mov_b32 m0, s78
	s_nop 0
	global_load_lds_dwordx4 v[158:159], off
	s_waitcnt vmcnt(8)
	s_waitcnt lgkmcnt(0)
	s_barrier
	s_setprio 1
	s_waitcnt lgkmcnt(0)
	s_cmp_eq_u32 s96, 10
	s_cbranch_scc0 .Ldt_do6
	s_cmp_eq_u64 s[38:39], 0
	s_cbranch_scc1 .Ldt_sk6

.Ldt_sk7:
	s_setprio 0
	s_barrier
	s_add_i32 s49, s49, 2
	s_add_u32 s44, s44, 0x100
	s_addc_u32 s45, s45, 0
	s_cmp_gt_u32 s49, 13
	s_cbranch_scc0 .LBB0_1658
	s_and_b64 vcc, exec, s[24:25]
	s_cbranch_vccz .LBB0_1661
	s_barrier
